# ss-scaled epilogues (FFN-in swiglu, w_in, QKV): 8 row-statistics loads issued up front, no per-block vmcnt(0) drain
# speedup vs baseline: 1.0116x; 1.0080x over previous
.LBB0_467:
	s_lshl_b32 s40, s68, 8
	s_cmp_lt_i32 s34, 64
	s_movk_i32 s21, 0x1600
	s_cselect_b32 s21, s21, 0x2c00
	s_cmp_gt_i32 s34, 31
	v_lshl_add_u32 v172, s34, 8, v164
	s_cselect_b32 s21, s21, 0
	s_lshl_b32 s21, s21, 2
	v_ashrrev_i32_e32 v173, 31, v172
	s_add_u32 s21, s57, s21
	v_lshl_add_u64 v[160:161], v[172:173], 2, s[14:15]
	s_addc_u32 s23, s58, 0
	s_ashr_i32 s41, s40, 31
	global_load_dword v177, v[160:161], off
	global_load_dword v241, v[160:161], off offset:64
	global_load_dword v242, v[160:161], off offset:128
	global_load_dword v243, v[160:161], off offset:192
	global_load_dword v244, v[160:161], off offset:512
	global_load_dword v245, v[160:161], off offset:576
	global_load_dword v246, v[160:161], off offset:640
	global_load_dword v247, v[160:161], off offset:704
	s_lshl_b64 s[44:45], s[40:41], 2
	s_add_u32 s21, s21, s44
	s_addc_u32 s23, s23, s45
	s_add_u32 s44, s21, s64
	s_addc_u32 s45, s23, 0
	global_load_dwordx4 v[140:143], v170, s[44:45]
	global_load_dwordx4 v[136:139], v170, s[44:45] offset:16
	global_load_dwordx4 v[132:135], v170, s[44:45] offset:512
	global_load_dwordx4 v[128:131], v170, s[44:45] offset:528
	v_lshlrev_b64 v[178:179], 11, v[172:173]
	v_or_b32_e32 v162, s40, v166
	v_ashrrev_i32_e32 v163, 31, v162
	v_or_b32_e32 v174, 16, v172
	v_lshl_add_u64 v[182:183], v[162:163], 1, s[36:37]
	v_ashrrev_i32_e32 v175, 31, v174
	v_lshl_add_u64 v[162:163], v[182:183], 0, v[178:179]
	v_lshl_add_u64 v[184:185], v[174:175], 2, s[14:15]
	s_mov_b32 s21, 0x40000
	s_mov_b64 s[40:41], 0x40000
	s_waitcnt vmcnt(0)
	v_fmamk_f32 v173, v177, 0x3a800000, v171
	v_rsq_f32_e32 v180, v173
	s_nop 0
	v_pk_fma_f32 v[126:127], v[126:127], v[180:181], v[142:143] op_sel_hi:[1,0,1]
	v_pk_fma_f32 v[124:125], v[124:125], v[180:181], v[140:141] op_sel_hi:[1,0,1]
	v_pk_fma_f32 v[122:123], v[122:123], v[180:181], v[138:139] op_sel_hi:[1,0,1]
	v_pk_fma_f32 v[120:121], v[120:121], v[180:181], v[136:137] op_sel_hi:[1,0,1]
	v_pk_fma_f32 v[118:119], v[118:119], v[180:181], v[134:135] op_sel_hi:[1,0,1]
	v_pk_fma_f32 v[116:117], v[116:117], v[180:181], v[132:133] op_sel_hi:[1,0,1]
	v_pk_fma_f32 v[178:179], v[114:115], v[180:181], v[130:131] op_sel_hi:[1,0,1]
	v_pk_fma_f32 v[180:181], v[112:113], v[180:181], v[128:129] op_sel_hi:[1,0,1]
	v_cvt_pk_f16_f32 v112, v124, v125
	v_cvt_pk_f16_f32 v113, v126, v127
	v_cvt_pk_f16_f32 v114, v120, v121
	v_cvt_pk_f16_f32 v115, v122, v123
	v_cvt_pk_f16_f32 v116, v116, v117
	v_cvt_pk_f16_f32 v117, v118, v119
	v_cvt_pk_f16_f32 v118, v180, v181
	v_cvt_pk_f16_f32 v119, v178, v179
	global_store_dwordx4 v[162:163], v[112:115], off
	global_store_dwordx4 v[162:163], v[116:119], off offset:256
	s_nop 0
	v_or_b32_e32 v112, 32, v172
	v_lshlrev_b64 v[116:117], 11, v[174:175]
	v_ashrrev_i32_e32 v113, 31, v112
	v_lshl_add_u64 v[116:117], v[182:183], 0, v[116:117]
	v_lshl_add_u64 v[118:119], v[112:113], 2, s[14:15]
	v_fmamk_f32 v114, v241, 0x3a800000, v171
	v_rsq_f32_e32 v114, v114
	s_nop 0
	v_pk_fma_f32 v[110:111], v[110:111], v[114:115], v[142:143] op_sel_hi:[1,0,1]
	v_pk_fma_f32 v[108:109], v[108:109], v[114:115], v[140:141] op_sel_hi:[1,0,1]
	v_pk_fma_f32 v[106:107], v[106:107], v[114:115], v[138:139] op_sel_hi:[1,0,1]
	v_pk_fma_f32 v[104:105], v[104:105], v[114:115], v[136:137] op_sel_hi:[1,0,1]
	v_pk_fma_f32 v[102:103], v[102:103], v[114:115], v[134:135] op_sel_hi:[1,0,1]
	v_pk_fma_f32 v[100:101], v[100:101], v[114:115], v[132:133] op_sel_hi:[1,0,1]
	v_pk_fma_f32 v[120:121], v[98:99], v[114:115], v[130:131] op_sel_hi:[1,0,1]
	v_pk_fma_f32 v[114:115], v[96:97], v[114:115], v[128:129] op_sel_hi:[1,0,1]
	v_cvt_pk_f16_f32 v96, v108, v109
	v_cvt_pk_f16_f32 v97, v110, v111
	v_cvt_pk_f16_f32 v98, v104, v105
	v_cvt_pk_f16_f32 v99, v106, v107
	v_cvt_pk_f16_f32 v100, v100, v101
	v_cvt_pk_f16_f32 v101, v102, v103
	v_cvt_pk_f16_f32 v102, v114, v115
	v_cvt_pk_f16_f32 v103, v120, v121
	global_store_dwordx4 v[116:117], v[96:99], off
	global_store_dwordx4 v[116:117], v[100:103], off offset:256
	s_nop 0
	v_or_b32_e32 v96, 48, v172
	v_lshlrev_b64 v[100:101], 11, v[112:113]
	v_ashrrev_i32_e32 v97, 31, v96
	v_lshl_add_u64 v[100:101], v[182:183], 0, v[100:101]
	v_lshl_add_u64 v[102:103], v[96:97], 2, s[14:15]
	v_fmamk_f32 v98, v242, 0x3a800000, v171
	v_rsq_f32_e32 v98, v98
	s_nop 0
	v_pk_fma_f32 v[94:95], v[94:95], v[98:99], v[142:143] op_sel_hi:[1,0,1]
	v_pk_fma_f32 v[92:93], v[92:93], v[98:99], v[140:141] op_sel_hi:[1,0,1]
	v_pk_fma_f32 v[90:91], v[90:91], v[98:99], v[138:139] op_sel_hi:[1,0,1]
	v_pk_fma_f32 v[88:89], v[88:89], v[98:99], v[136:137] op_sel_hi:[1,0,1]
	v_pk_fma_f32 v[82:83], v[82:83], v[98:99], v[134:135] op_sel_hi:[1,0,1]
	v_pk_fma_f32 v[80:81], v[80:81], v[98:99], v[132:133] op_sel_hi:[1,0,1]
	v_pk_fma_f32 v[104:105], v[74:75], v[98:99], v[130:131] op_sel_hi:[1,0,1]
	v_pk_fma_f32 v[98:99], v[72:73], v[98:99], v[128:129] op_sel_hi:[1,0,1]
	v_cvt_pk_f16_f32 v72, v92, v93
	v_cvt_pk_f16_f32 v73, v94, v95
	v_cvt_pk_f16_f32 v74, v88, v89
	v_cvt_pk_f16_f32 v75, v90, v91
	v_cvt_pk_f16_f32 v80, v80, v81
	v_cvt_pk_f16_f32 v81, v82, v83
	v_cvt_pk_f16_f32 v82, v98, v99
	v_cvt_pk_f16_f32 v83, v104, v105
	global_store_dwordx4 v[100:101], v[72:75], off
	global_store_dwordx4 v[100:101], v[80:83], off offset:256
	s_nop 0
	v_lshlrev_b64 v[74:75], 11, v[96:97]
	v_lshl_add_u64 v[74:75], v[182:183], 0, v[74:75]
	v_fmamk_f32 v72, v243, 0x3a800000, v171
	v_rsq_f32_e32 v72, v72
	s_nop 0
	v_pk_fma_f32 v[80:81], v[86:87], v[72:73], v[142:143] op_sel_hi:[1,0,1]
	v_pk_fma_f32 v[82:83], v[84:85], v[72:73], v[140:141] op_sel_hi:[1,0,1]
	v_pk_fma_f32 v[78:79], v[78:79], v[72:73], v[138:139] op_sel_hi:[1,0,1]
	v_pk_fma_f32 v[76:77], v[76:77], v[72:73], v[136:137] op_sel_hi:[1,0,1]
	v_pk_fma_f32 v[70:71], v[70:71], v[72:73], v[134:135] op_sel_hi:[1,0,1]
	v_pk_fma_f32 v[68:69], v[68:69], v[72:73], v[132:133] op_sel_hi:[1,0,1]
	v_pk_fma_f32 v[84:85], v[66:67], v[72:73], v[130:131] op_sel_hi:[1,0,1]
	v_pk_fma_f32 v[72:73], v[64:65], v[72:73], v[128:129] op_sel_hi:[1,0,1]
	v_cvt_pk_f16_f32 v64, v82, v83
	v_cvt_pk_f16_f32 v65, v80, v81
	v_cvt_pk_f16_f32 v66, v76, v77
	v_cvt_pk_f16_f32 v67, v78, v79
	v_cvt_pk_f16_f32 v68, v68, v69
	v_cvt_pk_f16_f32 v69, v70, v71
	v_cvt_pk_f16_f32 v70, v72, v73
	v_cvt_pk_f16_f32 v71, v84, v85
	global_store_dwordx4 v[74:75], v[64:67], off
	global_store_dwordx4 v[74:75], v[68:71], off offset:256
	s_nop 0
	v_lshl_add_u64 v[64:65], v[162:163], 0, s[40:41]
	v_add_co_u32_e32 v68, vcc, s21, v162
	s_mov_b64 s[40:41], 0x48000
	s_nop 0
	v_addc_co_u32_e32 v69, vcc, 0, v163, vcc
	v_fmamk_f32 v66, v244, 0x3a800000, v171
	v_rsq_f32_e32 v66, v66
	s_nop 0
	v_pk_fma_f32 v[62:63], v[62:63], v[66:67], v[142:143] op_sel_hi:[1,0,1]
	v_pk_fma_f32 v[60:61], v[60:61], v[66:67], v[140:141] op_sel_hi:[1,0,1]
	v_pk_fma_f32 v[58:59], v[58:59], v[66:67], v[138:139] op_sel_hi:[1,0,1]
	v_pk_fma_f32 v[56:57], v[56:57], v[66:67], v[136:137] op_sel_hi:[1,0,1]
	v_pk_fma_f32 v[54:55], v[54:55], v[66:67], v[134:135] op_sel_hi:[1,0,1]
	v_pk_fma_f32 v[52:53], v[52:53], v[66:67], v[132:133] op_sel_hi:[1,0,1]
	v_pk_fma_f32 v[70:71], v[50:51], v[66:67], v[130:131] op_sel_hi:[1,0,1]
	v_pk_fma_f32 v[66:67], v[48:49], v[66:67], v[128:129] op_sel_hi:[1,0,1]
	v_cvt_pk_f16_f32 v48, v60, v61
	v_cvt_pk_f16_f32 v49, v62, v63
	v_cvt_pk_f16_f32 v50, v56, v57
	v_cvt_pk_f16_f32 v51, v58, v59
	v_cvt_pk_f16_f32 v52, v52, v53
	v_cvt_pk_f16_f32 v53, v54, v55
	v_cvt_pk_f16_f32 v54, v66, v67
	v_cvt_pk_f16_f32 v55, v70, v71
	global_store_dwordx4 v[68:69], v[48:51], off
	global_store_dwordx4 v[64:65], v[52:55], off offset:256
	s_nop 0
	v_lshl_add_u64 v[48:49], v[162:163], 0, s[40:41]
	v_add_co_u32_e32 v52, vcc, s65, v162
	v_fmamk_f32 v50, v245, 0x3a800000, v171
	v_rsq_f32_e32 v50, v50
	v_addc_co_u32_e32 v53, vcc, 0, v163, vcc
	v_pk_fma_f32 v[46:47], v[46:47], v[50:51], v[142:143] op_sel_hi:[1,0,1]
	v_pk_fma_f32 v[44:45], v[44:45], v[50:51], v[140:141] op_sel_hi:[1,0,1]
	v_pk_fma_f32 v[42:43], v[42:43], v[50:51], v[138:139] op_sel_hi:[1,0,1]
	v_pk_fma_f32 v[40:41], v[40:41], v[50:51], v[136:137] op_sel_hi:[1,0,1]
	v_pk_fma_f32 v[38:39], v[38:39], v[50:51], v[134:135] op_sel_hi:[1,0,1]
	v_pk_fma_f32 v[36:37], v[36:37], v[50:51], v[132:133] op_sel_hi:[1,0,1]
	v_pk_fma_f32 v[54:55], v[34:35], v[50:51], v[130:131] op_sel_hi:[1,0,1]
	v_pk_fma_f32 v[50:51], v[32:33], v[50:51], v[128:129] op_sel_hi:[1,0,1]
	v_cvt_pk_f16_f32 v32, v44, v45
	v_cvt_pk_f16_f32 v33, v46, v47
	v_cvt_pk_f16_f32 v34, v40, v41
	v_cvt_pk_f16_f32 v35, v42, v43
	v_cvt_pk_f16_f32 v36, v36, v37
	v_cvt_pk_f16_f32 v37, v38, v39
	v_cvt_pk_f16_f32 v38, v50, v51
	v_cvt_pk_f16_f32 v39, v54, v55
	global_store_dwordx4 v[52:53], v[32:35], off
	global_store_dwordx4 v[48:49], v[36:39], off offset:256
	s_nop 0
	v_lshl_add_u64 v[32:33], v[162:163], 0, s[16:17]
	v_add_co_u32_e32 v36, vcc, s66, v162
	v_fmamk_f32 v34, v246, 0x3a800000, v171
	v_rsq_f32_e32 v34, v34
	v_addc_co_u32_e32 v37, vcc, 0, v163, vcc
	v_pk_fma_f32 v[30:31], v[30:31], v[34:35], v[142:143] op_sel_hi:[1,0,1]
	v_pk_fma_f32 v[28:29], v[28:29], v[34:35], v[140:141] op_sel_hi:[1,0,1]
	v_pk_fma_f32 v[26:27], v[26:27], v[34:35], v[138:139] op_sel_hi:[1,0,1]
	v_pk_fma_f32 v[24:25], v[24:25], v[34:35], v[136:137] op_sel_hi:[1,0,1]
	v_pk_fma_f32 v[22:23], v[22:23], v[34:35], v[134:135] op_sel_hi:[1,0,1]
	v_pk_fma_f32 v[20:21], v[20:21], v[34:35], v[132:133] op_sel_hi:[1,0,1]
	v_pk_fma_f32 v[38:39], v[18:19], v[34:35], v[130:131] op_sel_hi:[1,0,1]
	v_pk_fma_f32 v[34:35], v[16:17], v[34:35], v[128:129] op_sel_hi:[1,0,1]
	v_cvt_pk_f16_f32 v16, v28, v29
	v_cvt_pk_f16_f32 v17, v30, v31
	v_cvt_pk_f16_f32 v18, v24, v25
	v_cvt_pk_f16_f32 v19, v26, v27
	v_cvt_pk_f16_f32 v20, v20, v21
	v_cvt_pk_f16_f32 v21, v22, v23
	v_cvt_pk_f16_f32 v22, v34, v35
	v_cvt_pk_f16_f32 v23, v38, v39
	global_store_dwordx4 v[36:37], v[16:19], off
	global_store_dwordx4 v[32:33], v[20:23], off offset:256
	s_nop 0
	v_lshl_add_u64 v[16:17], v[162:163], 0, s[18:19]
	v_add_co_u32_e32 v20, vcc, s67, v162
	v_fmamk_f32 v18, v247, 0x3a800000, v171
	v_rsq_f32_e32 v18, v18
	v_addc_co_u32_e32 v21, vcc, 0, v163, vcc
	s_andn2_b64 vcc, exec, s[2:3]
	v_pk_fma_f32 v[14:15], v[14:15], v[18:19], v[142:143] op_sel_hi:[1,0,1]
	v_pk_fma_f32 v[12:13], v[12:13], v[18:19], v[140:141] op_sel_hi:[1,0,1]
	v_pk_fma_f32 v[10:11], v[10:11], v[18:19], v[138:139] op_sel_hi:[1,0,1]
	v_pk_fma_f32 v[8:9], v[8:9], v[18:19], v[136:137] op_sel_hi:[1,0,1]
	v_pk_fma_f32 v[6:7], v[6:7], v[18:19], v[134:135] op_sel_hi:[1,0,1]
	v_pk_fma_f32 v[4:5], v[4:5], v[18:19], v[132:133] op_sel_hi:[1,0,1]
	v_pk_fma_f32 v[22:23], v[2:3], v[18:19], v[130:131] op_sel_hi:[1,0,1]
	v_pk_fma_f32 v[18:19], v[0:1], v[18:19], v[128:129] op_sel_hi:[1,0,1]
	v_cvt_pk_f16_f32 v0, v12, v13
	v_cvt_pk_f16_f32 v1, v14, v15
	v_cvt_pk_f16_f32 v2, v8, v9
	v_cvt_pk_f16_f32 v3, v10, v11
	s_mov_b64 s[2:3], -1
	v_cvt_pk_f16_f32 v4, v4, v5
	v_cvt_pk_f16_f32 v5, v6, v7
	v_cvt_pk_f16_f32 v6, v18, v19
	v_cvt_pk_f16_f32 v7, v22, v23
	global_store_dwordx4 v[20:21], v[0:3], off
	global_store_dwordx4 v[16:17], v[4:7], off offset:256
	s_cbranch_vccnz .LBB0_456
	s_andn2_b64 vcc, exec, s[0:1]
	s_cbranch_vccnz .LBB0_455
	s_barrier
	s_branch .LBB0_455

.LBB0_1336:
	s_lshl_b32 s46, s1, 8
	s_cmp_lt_i32 s0, 64
	s_cselect_b32 s27, s66, 0x2c00
	s_cmp_gt_i32 s0, 31
	v_lshl_add_u32 v172, s0, 8, v164
	s_cselect_b32 s0, s27, 0
	s_lshl_b32 s0, s0, 2
	v_ashrrev_i32_e32 v173, 31, v172
	s_add_u32 s0, s59, s0
	v_lshl_add_u64 v[160:161], v[172:173], 2, s[20:21]
	s_addc_u32 s27, s60, 0
	s_ashr_i32 s47, s46, 31
	global_load_dword v177, v[160:161], off
	global_load_dword v241, v[160:161], off offset:64
	global_load_dword v242, v[160:161], off offset:128
	global_load_dword v243, v[160:161], off offset:192
	global_load_dword v244, v[160:161], off offset:512
	global_load_dword v245, v[160:161], off offset:576
	global_load_dword v246, v[160:161], off offset:640
	global_load_dword v247, v[160:161], off offset:704
	s_lshl_b64 s[48:49], s[46:47], 2
	s_add_u32 s0, s0, s48
	s_addc_u32 s27, s27, s49
	s_add_u32 s48, s0, s67
	s_addc_u32 s49, s27, 0
	global_load_dwordx4 v[140:143], v170, s[48:49]
	global_load_dwordx4 v[136:139], v170, s[48:49] offset:16
	global_load_dwordx4 v[132:135], v170, s[48:49] offset:512
	global_load_dwordx4 v[128:131], v170, s[48:49] offset:528
	s_ashr_i32 s0, s1, 31
	s_lshr_b32 s0, s0, 30
	s_add_i32 s0, s1, s0
	s_ashr_i32 s27, s0, 2
	s_mul_i32 s0, s27, 0x2100000
	v_lshlrev_b64 v[162:163], 11, v[172:173]
	s_mul_hi_i32 s1, s27, 0x2100000
	s_add_u32 s0, s36, s0
	s_addc_u32 s1, s37, s1
	s_lshl_b32 s27, s27, 10
	s_sub_i32 s27, s46, s27
	v_or_b32_e32 v180, s27, v166
	v_ashrrev_i32_e32 v181, 31, v180
	v_or_b32_e32 v174, 16, v172
	v_lshl_add_u64 v[180:181], v[180:181], 1, s[0:1]
	v_ashrrev_i32_e32 v175, 31, v174
	v_lshl_add_u64 v[162:163], v[180:181], 0, v[162:163]
	v_lshl_add_u64 v[178:179], v[174:175], 2, s[20:21]
	s_waitcnt vmcnt(0)
	v_fmamk_f32 v173, v177, 0x3a800000, v171
	v_rsq_f32_e32 v182, v173
	s_nop 0
	v_pk_fma_f32 v[126:127], v[126:127], v[182:183], v[142:143] op_sel_hi:[1,0,1]
	v_pk_fma_f32 v[124:125], v[124:125], v[182:183], v[140:141] op_sel_hi:[1,0,1]
	v_pk_fma_f32 v[122:123], v[122:123], v[182:183], v[138:139] op_sel_hi:[1,0,1]
	v_pk_fma_f32 v[120:121], v[120:121], v[182:183], v[136:137] op_sel_hi:[1,0,1]
	v_pk_fma_f32 v[118:119], v[118:119], v[182:183], v[134:135] op_sel_hi:[1,0,1]
	v_pk_fma_f32 v[116:117], v[116:117], v[182:183], v[132:133] op_sel_hi:[1,0,1]
	v_pk_fma_f32 v[184:185], v[114:115], v[182:183], v[130:131] op_sel_hi:[1,0,1]
	v_pk_fma_f32 v[182:183], v[112:113], v[182:183], v[128:129] op_sel_hi:[1,0,1]
	v_cvt_pk_f16_f32 v112, v124, v125
	v_cvt_pk_f16_f32 v113, v126, v127
	v_cvt_pk_f16_f32 v114, v120, v121
	v_cvt_pk_f16_f32 v115, v122, v123
	v_cvt_pk_f16_f32 v116, v116, v117
	v_cvt_pk_f16_f32 v117, v118, v119
	v_cvt_pk_f16_f32 v118, v182, v183
	v_cvt_pk_f16_f32 v119, v184, v185
	global_store_dwordx4 v[162:163], v[112:115], off
	global_store_dwordx4 v[162:163], v[116:119], off offset:256
	s_nop 0
	v_or_b32_e32 v112, 32, v172
	v_lshlrev_b64 v[116:117], 11, v[174:175]
	v_ashrrev_i32_e32 v113, 31, v112
	v_lshl_add_u64 v[116:117], v[180:181], 0, v[116:117]
	v_lshl_add_u64 v[118:119], v[112:113], 2, s[20:21]
	v_fmamk_f32 v114, v241, 0x3a800000, v171
	v_rsq_f32_e32 v114, v114
	s_nop 0
	v_pk_fma_f32 v[110:111], v[110:111], v[114:115], v[142:143] op_sel_hi:[1,0,1]
	v_pk_fma_f32 v[108:109], v[108:109], v[114:115], v[140:141] op_sel_hi:[1,0,1]
	v_pk_fma_f32 v[106:107], v[106:107], v[114:115], v[138:139] op_sel_hi:[1,0,1]
	v_pk_fma_f32 v[104:105], v[104:105], v[114:115], v[136:137] op_sel_hi:[1,0,1]
	v_pk_fma_f32 v[102:103], v[102:103], v[114:115], v[134:135] op_sel_hi:[1,0,1]
	v_pk_fma_f32 v[100:101], v[100:101], v[114:115], v[132:133] op_sel_hi:[1,0,1]
	v_pk_fma_f32 v[120:121], v[98:99], v[114:115], v[130:131] op_sel_hi:[1,0,1]
	v_pk_fma_f32 v[114:115], v[96:97], v[114:115], v[128:129] op_sel_hi:[1,0,1]
	v_cvt_pk_f16_f32 v96, v108, v109
	v_cvt_pk_f16_f32 v97, v110, v111
	v_cvt_pk_f16_f32 v98, v104, v105
	v_cvt_pk_f16_f32 v99, v106, v107
	v_cvt_pk_f16_f32 v100, v100, v101
	v_cvt_pk_f16_f32 v101, v102, v103
	v_cvt_pk_f16_f32 v102, v114, v115
	v_cvt_pk_f16_f32 v103, v120, v121
	global_store_dwordx4 v[116:117], v[96:99], off
	global_store_dwordx4 v[116:117], v[100:103], off offset:256
	s_nop 0
	v_or_b32_e32 v96, 48, v172
	v_lshlrev_b64 v[100:101], 11, v[112:113]
	v_ashrrev_i32_e32 v97, 31, v96
	v_lshl_add_u64 v[100:101], v[180:181], 0, v[100:101]
	v_lshl_add_u64 v[102:103], v[96:97], 2, s[20:21]
	v_fmamk_f32 v98, v242, 0x3a800000, v171
	v_rsq_f32_e32 v98, v98
	s_nop 0
	v_pk_fma_f32 v[94:95], v[94:95], v[98:99], v[142:143] op_sel_hi:[1,0,1]
	v_pk_fma_f32 v[92:93], v[92:93], v[98:99], v[140:141] op_sel_hi:[1,0,1]
	v_pk_fma_f32 v[90:91], v[90:91], v[98:99], v[138:139] op_sel_hi:[1,0,1]
	v_pk_fma_f32 v[88:89], v[88:89], v[98:99], v[136:137] op_sel_hi:[1,0,1]
	v_pk_fma_f32 v[82:83], v[82:83], v[98:99], v[134:135] op_sel_hi:[1,0,1]
	v_pk_fma_f32 v[80:81], v[80:81], v[98:99], v[132:133] op_sel_hi:[1,0,1]
	v_pk_fma_f32 v[104:105], v[74:75], v[98:99], v[130:131] op_sel_hi:[1,0,1]
	v_pk_fma_f32 v[98:99], v[72:73], v[98:99], v[128:129] op_sel_hi:[1,0,1]
	v_cvt_pk_f16_f32 v72, v92, v93
	v_cvt_pk_f16_f32 v73, v94, v95
	v_cvt_pk_f16_f32 v74, v88, v89
	v_cvt_pk_f16_f32 v75, v90, v91
	v_cvt_pk_f16_f32 v80, v80, v81
	v_cvt_pk_f16_f32 v81, v82, v83
	v_cvt_pk_f16_f32 v82, v98, v99
	v_cvt_pk_f16_f32 v83, v104, v105
	global_store_dwordx4 v[100:101], v[72:75], off
	global_store_dwordx4 v[100:101], v[80:83], off offset:256
	s_nop 0
	v_lshlrev_b64 v[74:75], 11, v[96:97]
	v_lshl_add_u64 v[74:75], v[180:181], 0, v[74:75]
	v_fmamk_f32 v72, v243, 0x3a800000, v171
	v_rsq_f32_e32 v72, v72
	s_nop 0
	v_pk_fma_f32 v[80:81], v[86:87], v[72:73], v[142:143] op_sel_hi:[1,0,1]
	v_pk_fma_f32 v[82:83], v[84:85], v[72:73], v[140:141] op_sel_hi:[1,0,1]
	v_pk_fma_f32 v[78:79], v[78:79], v[72:73], v[138:139] op_sel_hi:[1,0,1]
	v_pk_fma_f32 v[76:77], v[76:77], v[72:73], v[136:137] op_sel_hi:[1,0,1]
	v_pk_fma_f32 v[70:71], v[70:71], v[72:73], v[134:135] op_sel_hi:[1,0,1]
	v_pk_fma_f32 v[68:69], v[68:69], v[72:73], v[132:133] op_sel_hi:[1,0,1]
	v_pk_fma_f32 v[84:85], v[66:67], v[72:73], v[130:131] op_sel_hi:[1,0,1]
	v_pk_fma_f32 v[72:73], v[64:65], v[72:73], v[128:129] op_sel_hi:[1,0,1]
	v_cvt_pk_f16_f32 v64, v82, v83
	v_cvt_pk_f16_f32 v65, v80, v81
	v_cvt_pk_f16_f32 v66, v76, v77
	v_cvt_pk_f16_f32 v67, v78, v79
	v_cvt_pk_f16_f32 v68, v68, v69
	v_cvt_pk_f16_f32 v69, v70, v71
	v_cvt_pk_f16_f32 v70, v72, v73
	v_cvt_pk_f16_f32 v71, v84, v85
	global_store_dwordx4 v[74:75], v[64:67], off
	global_store_dwordx4 v[74:75], v[68:71], off offset:256
	s_nop 0
	v_lshl_add_u64 v[64:65], v[162:163], 0, s[4:5]
	v_add_co_u32_e32 v68, vcc, s68, v162
	v_fmamk_f32 v66, v244, 0x3a800000, v171
	v_rsq_f32_e32 v66, v66
	v_addc_co_u32_e32 v69, vcc, 0, v163, vcc
	v_pk_fma_f32 v[62:63], v[62:63], v[66:67], v[142:143] op_sel_hi:[1,0,1]
	v_pk_fma_f32 v[60:61], v[60:61], v[66:67], v[140:141] op_sel_hi:[1,0,1]
	v_pk_fma_f32 v[58:59], v[58:59], v[66:67], v[138:139] op_sel_hi:[1,0,1]
	v_pk_fma_f32 v[56:57], v[56:57], v[66:67], v[136:137] op_sel_hi:[1,0,1]
	v_pk_fma_f32 v[54:55], v[54:55], v[66:67], v[134:135] op_sel_hi:[1,0,1]
	v_pk_fma_f32 v[52:53], v[52:53], v[66:67], v[132:133] op_sel_hi:[1,0,1]
	v_pk_fma_f32 v[70:71], v[50:51], v[66:67], v[130:131] op_sel_hi:[1,0,1]
	v_pk_fma_f32 v[66:67], v[48:49], v[66:67], v[128:129] op_sel_hi:[1,0,1]
	v_cvt_pk_f16_f32 v48, v60, v61
	v_cvt_pk_f16_f32 v49, v62, v63
	v_cvt_pk_f16_f32 v50, v56, v57
	v_cvt_pk_f16_f32 v51, v58, v59
	v_cvt_pk_f16_f32 v52, v52, v53
	v_cvt_pk_f16_f32 v53, v54, v55
	v_cvt_pk_f16_f32 v54, v66, v67
	v_cvt_pk_f16_f32 v55, v70, v71
	global_store_dwordx4 v[68:69], v[48:51], off
	global_store_dwordx4 v[64:65], v[52:55], off offset:256
	s_nop 0
	v_lshl_add_u64 v[48:49], v[162:163], 0, s[16:17]
	v_add_co_u32_e32 v52, vcc, s69, v162
	v_fmamk_f32 v50, v245, 0x3a800000, v171
	v_rsq_f32_e32 v50, v50
	v_addc_co_u32_e32 v53, vcc, 0, v163, vcc
	v_pk_fma_f32 v[46:47], v[46:47], v[50:51], v[142:143] op_sel_hi:[1,0,1]
	v_pk_fma_f32 v[44:45], v[44:45], v[50:51], v[140:141] op_sel_hi:[1,0,1]
	v_pk_fma_f32 v[42:43], v[42:43], v[50:51], v[138:139] op_sel_hi:[1,0,1]
	v_pk_fma_f32 v[40:41], v[40:41], v[50:51], v[136:137] op_sel_hi:[1,0,1]
	v_pk_fma_f32 v[38:39], v[38:39], v[50:51], v[134:135] op_sel_hi:[1,0,1]
	v_pk_fma_f32 v[36:37], v[36:37], v[50:51], v[132:133] op_sel_hi:[1,0,1]
	v_pk_fma_f32 v[54:55], v[34:35], v[50:51], v[130:131] op_sel_hi:[1,0,1]
	v_pk_fma_f32 v[50:51], v[32:33], v[50:51], v[128:129] op_sel_hi:[1,0,1]
	v_cvt_pk_f16_f32 v32, v44, v45
	v_cvt_pk_f16_f32 v33, v46, v47
	v_cvt_pk_f16_f32 v34, v40, v41
	v_cvt_pk_f16_f32 v35, v42, v43
	v_cvt_pk_f16_f32 v36, v36, v37
	v_cvt_pk_f16_f32 v37, v38, v39
	v_cvt_pk_f16_f32 v38, v50, v51
	v_cvt_pk_f16_f32 v39, v54, v55
	global_store_dwordx4 v[52:53], v[32:35], off
	global_store_dwordx4 v[48:49], v[36:39], off offset:256
	s_nop 0
	v_lshl_add_u64 v[32:33], v[162:163], 0, s[18:19]
	v_add_co_u32_e32 v36, vcc, s70, v162
	v_fmamk_f32 v34, v246, 0x3a800000, v171
	v_rsq_f32_e32 v34, v34
	v_addc_co_u32_e32 v37, vcc, 0, v163, vcc
	s_andn2_b64 vcc, exec, s[2:3]
	v_pk_fma_f32 v[30:31], v[30:31], v[34:35], v[142:143] op_sel_hi:[1,0,1]
	v_pk_fma_f32 v[28:29], v[28:29], v[34:35], v[140:141] op_sel_hi:[1,0,1]
	v_pk_fma_f32 v[26:27], v[26:27], v[34:35], v[138:139] op_sel_hi:[1,0,1]
	v_pk_fma_f32 v[24:25], v[24:25], v[34:35], v[136:137] op_sel_hi:[1,0,1]
	v_pk_fma_f32 v[22:23], v[22:23], v[34:35], v[134:135] op_sel_hi:[1,0,1]
	v_pk_fma_f32 v[20:21], v[20:21], v[34:35], v[132:133] op_sel_hi:[1,0,1]
	v_pk_fma_f32 v[38:39], v[18:19], v[34:35], v[130:131] op_sel_hi:[1,0,1]
	v_pk_fma_f32 v[34:35], v[16:17], v[34:35], v[128:129] op_sel_hi:[1,0,1]
	v_cvt_pk_f16_f32 v16, v28, v29
	v_cvt_pk_f16_f32 v17, v30, v31
	v_cvt_pk_f16_f32 v18, v24, v25
	v_cvt_pk_f16_f32 v19, v26, v27
	v_cvt_pk_f16_f32 v20, v20, v21
	v_cvt_pk_f16_f32 v21, v22, v23
	v_cvt_pk_f16_f32 v22, v34, v35
	v_cvt_pk_f16_f32 v23, v38, v39
	global_store_dwordx4 v[36:37], v[16:19], off
	global_store_dwordx4 v[32:33], v[20:23], off offset:256
	s_nop 0
	v_lshl_add_u64 v[16:17], v[162:163], 0, s[24:25]
	v_add_co_u32_e64 v20, s[0:1], s71, v162
	v_fmamk_f32 v18, v247, 0x3a800000, v171
	v_rsq_f32_e32 v18, v18
	v_addc_co_u32_e64 v21, s[0:1], 0, v163, s[0:1]
	s_mov_b64 s[0:1], -1
	v_pk_fma_f32 v[14:15], v[14:15], v[18:19], v[142:143] op_sel_hi:[1,0,1]
	v_pk_fma_f32 v[12:13], v[12:13], v[18:19], v[140:141] op_sel_hi:[1,0,1]
	v_pk_fma_f32 v[10:11], v[10:11], v[18:19], v[138:139] op_sel_hi:[1,0,1]
	v_pk_fma_f32 v[8:9], v[8:9], v[18:19], v[136:137] op_sel_hi:[1,0,1]
	v_pk_fma_f32 v[6:7], v[6:7], v[18:19], v[134:135] op_sel_hi:[1,0,1]
	v_pk_fma_f32 v[4:5], v[4:5], v[18:19], v[132:133] op_sel_hi:[1,0,1]
	v_pk_fma_f32 v[22:23], v[2:3], v[18:19], v[130:131] op_sel_hi:[1,0,1]
	v_pk_fma_f32 v[18:19], v[0:1], v[18:19], v[128:129] op_sel_hi:[1,0,1]
	v_cvt_pk_f16_f32 v0, v12, v13
	v_cvt_pk_f16_f32 v1, v14, v15
	v_cvt_pk_f16_f32 v2, v8, v9
	v_cvt_pk_f16_f32 v3, v10, v11
	v_cvt_pk_f16_f32 v4, v4, v5
	v_cvt_pk_f16_f32 v5, v6, v7
	v_cvt_pk_f16_f32 v6, v18, v19
	v_cvt_pk_f16_f32 v7, v22, v23
	global_store_dwordx4 v[20:21], v[0:3], off
	global_store_dwordx4 v[16:17], v[4:7], off offset:256
	s_cbranch_vccnz .LBB0_1329
	s_andn2_b64 vcc, exec, s[10:11]
	s_cbranch_vccnz .LBB0_1328
	s_barrier
	s_branch .LBB0_1328
